# EpiLat epilogue hand-written with in-loop row-scale preload (on top of EpiUq/KvB/QkvA)
# speedup vs baseline: 1.0165x; 1.0008x over previous
.LBB0_126:
	s_add_u32 s0, s24, 0xfffc0080
	s_addc_u32 s38, s25, -1
	s_add_i32 s63, 0, 0x10000
	s_cmp_eq_u32 s73, 12
	s_cselect_b32 s41, s29, s38
	s_cselect_b32 s40, s42, s0
	v_add_u32_e32 v0, s63, v214
	s_cselect_b32 s39, s43, s71
	s_cselect_b32 s38, s54, s55
	s_add_i32 s0, 0, 0x14000
	ds_read_b128 v[130:133], v0
	ds_read_b128 v[142:145], v0 offset:1024
	ds_read_b128 v[146:149], v0 offset:2048
	ds_read_b128 v[150:153], v0 offset:3072
	v_add_u32_e32 v0, s0, v214
	ds_read_b128 v[154:157], v0
	ds_read_b128 v[158:161], v0 offset:1024
	ds_read_b128 v[162:165], v0 offset:2048
	ds_read_b128 v[166:169], v0 offset:3072
	s_cmp_eq_u32 s73, 12
	s_cbranch_scc0 .Llat_pa_skip
	v_and_b32_e32 v253, 15, v193
	v_lshl_add_u32 v252, s4, 8, v253
	v_add_u32_e32 v252, s89, v252
	v_bfe_u32 v253, v193, 4, 2
	v_lshlrev_b32_e32 v253, 4, v253
	v_mul_u32_u24_e32 v252, 0x40, v252
	v_add_u32_e32 v252, v252, v253
	global_load_dwordx4 v[194:197], v252, s[18:19]
	global_load_dwordx4 v[198:201], v252, s[18:19] offset:1024
	global_load_dwordx4 v[202:205], v252, s[18:19] offset:2048
	global_load_dwordx4 v[206:209], v252, s[18:19] offset:3072
.Llat_pa_skip:
	v_lshl_add_u64 v[190:191], s[24:25], 0, v[140:141]
	s_add_i32 m0, s84, 0xc000
	ds_read_b128 v[170:173], v215
	ds_read_b128 v[174:177], v215 offset:1024
	ds_read_b128 v[178:181], v215 offset:2048
	ds_read_b128 v[182:185], v215 offset:3072
	ds_read_b128 v[186:189], v215 offset:4096
	ds_read_b128 v[216:219], v215 offset:5120
	ds_read_b128 v[228:231], v215 offset:6144
	ds_read_b128 v[232:235], v215 offset:7168
	global_load_lds_dwordx4 v[190:191], off
	v_lshl_add_u64 v[190:191], s[24:25], 0, v[138:139]
	s_add_i32 m0, s84, 0xe000
	s_nop 0
	global_load_lds_dwordx4 v[190:191], off
	s_waitcnt vmcnt(8)
	s_waitcnt lgkmcnt(0)
	s_barrier
	s_setprio 1
	s_waitcnt lgkmcnt(0)
	v_mfma_f32_16x16x32_bf16 v[126:129], v[130:133], v[170:173], v[126:129]
	v_mfma_f32_16x16x32_bf16 v[122:125], v[146:149], v[170:173], v[122:125]
	v_mfma_f32_16x16x32_bf16 v[110:113], v[130:133], v[178:181], v[110:113]
	v_mfma_f32_16x16x32_bf16 v[106:109], v[146:149], v[178:181], v[106:109]
	v_mfma_f32_16x16x32_bf16 v[94:97], v[130:133], v[186:189], v[94:97]
	v_mfma_f32_16x16x32_bf16 v[90:93], v[146:149], v[186:189], v[90:93]
	v_mfma_f32_16x16x32_bf16 v[78:81], v[130:133], v[228:231], v[78:81]
	v_mfma_f32_16x16x32_bf16 v[74:77], v[146:149], v[228:231], v[74:77]
	v_mfma_f32_16x16x32_bf16 v[126:129], v[142:145], v[174:177], v[126:129]
	v_mfma_f32_16x16x32_bf16 v[122:125], v[150:153], v[174:177], v[122:125]
	v_mfma_f32_16x16x32_bf16 v[110:113], v[142:145], v[182:185], v[110:113]
	v_mfma_f32_16x16x32_bf16 v[106:109], v[150:153], v[182:185], v[106:109]
	v_mfma_f32_16x16x32_bf16 v[94:97], v[142:145], v[216:219], v[94:97]
	v_mfma_f32_16x16x32_bf16 v[90:93], v[150:153], v[216:219], v[90:93]
	v_mfma_f32_16x16x32_bf16 v[78:81], v[142:145], v[232:235], v[78:81]
	v_mfma_f32_16x16x32_bf16 v[74:77], v[150:153], v[232:235], v[74:77]
	s_setprio 0
	s_setprio 1
	v_mfma_f32_16x16x32_bf16 v[118:121], v[154:157], v[170:173], v[118:121]
	v_mfma_f32_16x16x32_bf16 v[114:117], v[162:165], v[170:173], v[114:117]
	v_mfma_f32_16x16x32_bf16 v[102:105], v[154:157], v[178:181], v[102:105]
	v_mfma_f32_16x16x32_bf16 v[98:101], v[162:165], v[178:181], v[98:101]
	v_mfma_f32_16x16x32_bf16 v[86:89], v[154:157], v[186:189], v[86:89]
	v_mfma_f32_16x16x32_bf16 v[82:85], v[162:165], v[186:189], v[82:85]
	v_mfma_f32_16x16x32_bf16 v[70:73], v[154:157], v[228:231], v[70:73]
	v_mfma_f32_16x16x32_bf16 v[66:69], v[162:165], v[228:231], v[66:69]
	v_mfma_f32_16x16x32_bf16 v[118:121], v[158:161], v[174:177], v[118:121]
	v_mfma_f32_16x16x32_bf16 v[114:117], v[166:169], v[174:177], v[114:117]
	v_mfma_f32_16x16x32_bf16 v[102:105], v[158:161], v[182:185], v[102:105]
	v_mfma_f32_16x16x32_bf16 v[98:101], v[166:169], v[182:185], v[98:101]
	v_mfma_f32_16x16x32_bf16 v[86:89], v[158:161], v[216:219], v[86:89]
	v_mfma_f32_16x16x32_bf16 v[82:85], v[166:169], v[216:219], v[82:85]
	v_mfma_f32_16x16x32_bf16 v[70:73], v[158:161], v[232:235], v[70:73]
	v_mfma_f32_16x16x32_bf16 v[66:69], v[166:169], v[232:235], v[66:69]
	s_setprio 0
	s_barrier
	s_add_i32 s63, s63, s83
	v_lshl_add_u64 v[190:191], s[38:39], 0, v[136:137]
	s_mov_b32 m0, s63
	ds_read_b128 v[170:173], v215 offset:16384
	ds_read_b128 v[174:177], v215 offset:17408
	ds_read_b128 v[178:181], v215 offset:18432
	ds_read_b128 v[182:185], v215 offset:19456
	ds_read_b128 v[186:189], v215 offset:20480
	ds_read_b128 v[216:219], v215 offset:21504
	ds_read_b128 v[228:231], v215 offset:22528
	ds_read_b128 v[232:235], v215 offset:23552
	global_load_lds_dwordx4 v[190:191], off
	s_add_i32 m0, s63, 0x2000
	s_add_u32 s64, s38, 0x40000
	v_lshl_add_u64 v[236:237], s[38:39], 0, v[134:135]
	s_addc_u32 s65, s39, 0
	s_add_i32 s0, s0, s83
	global_load_lds_dwordx4 v[236:237], off
	v_lshl_add_u64 v[238:239], s[64:65], 0, v[136:137]
	s_mov_b32 m0, s0
	v_lshl_add_u64 v[240:241], s[40:41], 0, v[134:135]
	global_load_lds_dwordx4 v[238:239], off
	v_lshl_add_u64 v[238:239], s[64:65], 0, v[134:135]
	s_add_i32 m0, s0, 0x2000
	s_nop 0
	global_load_lds_dwordx4 v[238:239], off
	v_lshl_add_u64 v[238:239], s[40:41], 0, v[136:137]
	s_mov_b32 m0, s84
	s_nop 0
	global_load_lds_dwordx4 v[238:239], off
	s_mov_b32 m0, s85
	s_nop 0
	global_load_lds_dwordx4 v[240:241], off
	s_waitcnt vmcnt(8)
	s_waitcnt lgkmcnt(0)
	s_barrier
	s_setprio 1
	s_waitcnt lgkmcnt(0)
	v_mfma_f32_16x16x32_bf16 v[62:65], v[130:133], v[170:173], v[62:65]
	v_mfma_f32_16x16x32_bf16 v[58:61], v[146:149], v[170:173], v[58:61]
	v_mfma_f32_16x16x32_bf16 v[46:49], v[130:133], v[178:181], v[46:49]
	v_mfma_f32_16x16x32_bf16 v[42:45], v[146:149], v[178:181], v[42:45]
	v_mfma_f32_16x16x32_bf16 v[30:33], v[130:133], v[186:189], v[30:33]
	v_mfma_f32_16x16x32_bf16 v[26:29], v[146:149], v[186:189], v[26:29]
	v_mfma_f32_16x16x32_bf16 v[14:17], v[130:133], v[228:231], v[14:17]
	v_mfma_f32_16x16x32_bf16 v[10:13], v[146:149], v[228:231], v[10:13]
	v_mfma_f32_16x16x32_bf16 v[62:65], v[142:145], v[174:177], v[62:65]
	v_mfma_f32_16x16x32_bf16 v[58:61], v[150:153], v[174:177], v[58:61]
	v_mfma_f32_16x16x32_bf16 v[46:49], v[142:145], v[182:185], v[46:49]
	v_mfma_f32_16x16x32_bf16 v[42:45], v[150:153], v[182:185], v[42:45]
	v_mfma_f32_16x16x32_bf16 v[30:33], v[142:145], v[216:219], v[30:33]
	v_mfma_f32_16x16x32_bf16 v[26:29], v[150:153], v[216:219], v[26:29]
	v_mfma_f32_16x16x32_bf16 v[14:17], v[142:145], v[232:235], v[14:17]
	v_mfma_f32_16x16x32_bf16 v[10:13], v[150:153], v[232:235], v[10:13]
	s_setprio 0
	s_setprio 1
	v_mfma_f32_16x16x32_bf16 v[54:57], v[154:157], v[170:173], v[54:57]
	v_mfma_f32_16x16x32_bf16 v[50:53], v[162:165], v[170:173], v[50:53]
	v_mfma_f32_16x16x32_bf16 v[38:41], v[154:157], v[178:181], v[38:41]
	v_mfma_f32_16x16x32_bf16 v[34:37], v[162:165], v[178:181], v[34:37]
	v_mfma_f32_16x16x32_bf16 v[22:25], v[154:157], v[186:189], v[22:25]
	v_mfma_f32_16x16x32_bf16 v[18:21], v[162:165], v[186:189], v[18:21]
	v_mfma_f32_16x16x32_bf16 v[6:9], v[154:157], v[228:231], v[6:9]
	v_mfma_f32_16x16x32_bf16 v[2:5], v[162:165], v[228:231], v[2:5]
	v_mfma_f32_16x16x32_bf16 v[54:57], v[158:161], v[174:177], v[54:57]
	v_mfma_f32_16x16x32_bf16 v[50:53], v[166:169], v[174:177], v[50:53]
	v_mfma_f32_16x16x32_bf16 v[38:41], v[158:161], v[182:185], v[38:41]
	v_mfma_f32_16x16x32_bf16 v[34:37], v[166:169], v[182:185], v[34:37]
	v_mfma_f32_16x16x32_bf16 v[22:25], v[158:161], v[216:219], v[22:25]
	v_mfma_f32_16x16x32_bf16 v[18:21], v[166:169], v[216:219], v[18:21]
	v_mfma_f32_16x16x32_bf16 v[6:9], v[158:161], v[232:235], v[6:9]
	v_mfma_f32_16x16x32_bf16 v[2:5], v[166:169], v[232:235], v[2:5]
	s_setprio 0
	s_barrier
	s_add_i32 s0, 0, 0x18000
	v_add_u32_e32 v0, s0, v214
	s_add_i32 s63, 0, 0x1c000
	ds_read_b128 v[130:133], v0
	ds_read_b128 v[142:145], v0 offset:1024
	ds_read_b128 v[146:149], v0 offset:2048
	ds_read_b128 v[150:153], v0 offset:3072
	v_add_u32_e32 v0, s63, v214
	ds_read_b128 v[154:157], v0
	ds_read_b128 v[158:161], v0 offset:1024
	ds_read_b128 v[162:165], v0 offset:2048
	ds_read_b128 v[166:169], v0 offset:3072
	s_add_u32 s40, s40, 0x40000
	s_addc_u32 s41, s41, 0
	s_mov_b32 m0, s86
	v_lshl_add_u64 v[242:243], s[40:41], 0, v[136:137]
	ds_read_b128 v[170:173], v215 offset:32768
	ds_read_b128 v[174:177], v215 offset:33792
	ds_read_b128 v[178:181], v215 offset:34816
	ds_read_b128 v[182:185], v215 offset:35840
	ds_read_b128 v[186:189], v215 offset:36864
	ds_read_b128 v[216:219], v215 offset:37888
	ds_read_b128 v[228:231], v215 offset:38912
	ds_read_b128 v[232:235], v215 offset:39936
	s_cmp_eq_u32 s73, 12
	s_cbranch_scc0 .Llat_pb_skip
	v_add_f32_e32 v221, v195, v194
	v_add_f32_e32 v253, v196, v197
	v_add_f32_e32 v221, v221, v253
	v_add_f32_e32 v222, v199, v198
	v_add_f32_e32 v253, v200, v201
	v_add_f32_e32 v222, v222, v253
	v_add_f32_e32 v223, v203, v202
	v_add_f32_e32 v253, v204, v205
	v_add_f32_e32 v223, v223, v253
	v_add_f32_e32 v224, v207, v206
	v_add_f32_e32 v253, v208, v209
	v_add_f32_e32 v224, v224, v253
	v_add_u32_e32 v253, 0x2000, v252
	global_load_dwordx4 v[194:197], v253, s[18:19]
	global_load_dwordx4 v[198:201], v253, s[18:19] offset:1024
	global_load_dwordx4 v[202:205], v253, s[18:19] offset:2048
	global_load_dwordx4 v[206:209], v253, s[18:19] offset:3072
.Llat_pb_skip:
	global_load_lds_dwordx4 v[242:243], off
	v_lshl_add_u64 v[242:243], s[40:41], 0, v[134:135]
	s_mov_b32 m0, s87
	s_nop 0
	global_load_lds_dwordx4 v[242:243], off
	s_waitcnt vmcnt(8)
	s_waitcnt lgkmcnt(0)
	s_barrier
	s_setprio 1
	s_waitcnt lgkmcnt(0)
	v_mfma_f32_16x16x32_bf16 v[126:129], v[130:133], v[170:173], v[126:129]
	v_mfma_f32_16x16x32_bf16 v[122:125], v[146:149], v[170:173], v[122:125]
	v_mfma_f32_16x16x32_bf16 v[110:113], v[130:133], v[178:181], v[110:113]
	v_mfma_f32_16x16x32_bf16 v[106:109], v[146:149], v[178:181], v[106:109]
	v_mfma_f32_16x16x32_bf16 v[94:97], v[130:133], v[186:189], v[94:97]
	v_mfma_f32_16x16x32_bf16 v[90:93], v[146:149], v[186:189], v[90:93]
	v_mfma_f32_16x16x32_bf16 v[78:81], v[130:133], v[228:231], v[78:81]
	v_mfma_f32_16x16x32_bf16 v[74:77], v[146:149], v[228:231], v[74:77]
	v_mfma_f32_16x16x32_bf16 v[126:129], v[142:145], v[174:177], v[126:129]
	v_mfma_f32_16x16x32_bf16 v[122:125], v[150:153], v[174:177], v[122:125]
	v_mfma_f32_16x16x32_bf16 v[110:113], v[142:145], v[182:185], v[110:113]
	v_mfma_f32_16x16x32_bf16 v[106:109], v[150:153], v[182:185], v[106:109]
	v_mfma_f32_16x16x32_bf16 v[94:97], v[142:145], v[216:219], v[94:97]
	v_mfma_f32_16x16x32_bf16 v[90:93], v[150:153], v[216:219], v[90:93]
	v_mfma_f32_16x16x32_bf16 v[78:81], v[142:145], v[232:235], v[78:81]
	v_mfma_f32_16x16x32_bf16 v[74:77], v[150:153], v[232:235], v[74:77]
	s_setprio 0
	s_setprio 1
	v_mfma_f32_16x16x32_bf16 v[118:121], v[154:157], v[170:173], v[118:121]
	v_mfma_f32_16x16x32_bf16 v[114:117], v[162:165], v[170:173], v[114:117]
	v_mfma_f32_16x16x32_bf16 v[102:105], v[154:157], v[178:181], v[102:105]
	v_mfma_f32_16x16x32_bf16 v[98:101], v[162:165], v[178:181], v[98:101]
	v_mfma_f32_16x16x32_bf16 v[86:89], v[154:157], v[186:189], v[86:89]
	v_mfma_f32_16x16x32_bf16 v[82:85], v[162:165], v[186:189], v[82:85]
	v_mfma_f32_16x16x32_bf16 v[70:73], v[154:157], v[228:231], v[70:73]
	v_mfma_f32_16x16x32_bf16 v[66:69], v[162:165], v[228:231], v[66:69]
	v_mfma_f32_16x16x32_bf16 v[118:121], v[158:161], v[174:177], v[118:121]
	v_mfma_f32_16x16x32_bf16 v[114:117], v[166:169], v[174:177], v[114:117]
	v_mfma_f32_16x16x32_bf16 v[102:105], v[158:161], v[182:185], v[102:105]
	v_mfma_f32_16x16x32_bf16 v[98:101], v[166:169], v[182:185], v[98:101]
	v_mfma_f32_16x16x32_bf16 v[86:89], v[158:161], v[216:219], v[86:89]
	v_mfma_f32_16x16x32_bf16 v[82:85], v[166:169], v[216:219], v[82:85]
	v_mfma_f32_16x16x32_bf16 v[70:73], v[158:161], v[232:235], v[70:73]
	v_mfma_f32_16x16x32_bf16 v[66:69], v[166:169], v[232:235], v[66:69]
	s_setprio 0
	s_barrier
	s_add_i32 s0, s0, s83
	v_lshl_add_u64 v[190:191], v[190:191], 0, s[52:53]
	s_mov_b32 m0, s0
	ds_read_b128 v[170:173], v215 offset:49152
	ds_read_b128 v[174:177], v215 offset:50176
	ds_read_b128 v[178:181], v215 offset:51200
	ds_read_b128 v[182:185], v215 offset:52224
	ds_read_b128 v[186:189], v215 offset:53248
	ds_read_b128 v[216:219], v215 offset:54272
	ds_read_b128 v[228:231], v215 offset:55296
	ds_read_b128 v[232:235], v215 offset:56320
	global_load_lds_dwordx4 v[190:191], off
	s_add_i32 m0, s0, 0x2000
	s_add_u32 s38, s38, 0x40080
	v_lshl_add_u64 v[190:191], v[236:237], 0, s[52:53]
	s_addc_u32 s39, s39, 0
	s_add_i32 s0, s63, s83
	global_load_lds_dwordx4 v[190:191], off
	v_lshl_add_u64 v[190:191], s[38:39], 0, v[136:137]
	s_mov_b32 m0, s0
	s_nop 0
	global_load_lds_dwordx4 v[190:191], off
	v_lshl_add_u64 v[190:191], s[38:39], 0, v[134:135]
	s_add_i32 m0, s0, 0x2000
	s_nop 0
	global_load_lds_dwordx4 v[190:191], off
	v_lshl_add_u64 v[190:191], v[238:239], 0, s[52:53]
	s_mov_b32 m0, s91
	s_nop 0
	global_load_lds_dwordx4 v[190:191], off
	v_lshl_add_u64 v[190:191], v[240:241], 0, s[52:53]
	s_mov_b32 m0, s92
	s_nop 0
	global_load_lds_dwordx4 v[190:191], off
	s_waitcnt vmcnt(8)
	s_waitcnt lgkmcnt(0)
	s_barrier
	s_setprio 1
	s_waitcnt lgkmcnt(0)
	v_mfma_f32_16x16x32_bf16 v[62:65], v[130:133], v[170:173], v[62:65]
	v_mfma_f32_16x16x32_bf16 v[58:61], v[146:149], v[170:173], v[58:61]
	v_mfma_f32_16x16x32_bf16 v[46:49], v[130:133], v[178:181], v[46:49]
	v_mfma_f32_16x16x32_bf16 v[42:45], v[146:149], v[178:181], v[42:45]
	v_mfma_f32_16x16x32_bf16 v[30:33], v[130:133], v[186:189], v[30:33]
	v_mfma_f32_16x16x32_bf16 v[26:29], v[146:149], v[186:189], v[26:29]
	v_mfma_f32_16x16x32_bf16 v[14:17], v[130:133], v[228:231], v[14:17]
	v_mfma_f32_16x16x32_bf16 v[10:13], v[146:149], v[228:231], v[10:13]
	v_mfma_f32_16x16x32_bf16 v[62:65], v[142:145], v[174:177], v[62:65]
	v_mfma_f32_16x16x32_bf16 v[58:61], v[150:153], v[174:177], v[58:61]
	v_mfma_f32_16x16x32_bf16 v[46:49], v[142:145], v[182:185], v[46:49]
	v_mfma_f32_16x16x32_bf16 v[42:45], v[150:153], v[182:185], v[42:45]
	v_mfma_f32_16x16x32_bf16 v[30:33], v[142:145], v[216:219], v[30:33]
	v_mfma_f32_16x16x32_bf16 v[26:29], v[150:153], v[216:219], v[26:29]
	v_mfma_f32_16x16x32_bf16 v[14:17], v[142:145], v[232:235], v[14:17]
	v_mfma_f32_16x16x32_bf16 v[10:13], v[150:153], v[232:235], v[10:13]
	s_setprio 0
	s_setprio 1
	v_mfma_f32_16x16x32_bf16 v[54:57], v[154:157], v[170:173], v[54:57]
	v_mfma_f32_16x16x32_bf16 v[50:53], v[162:165], v[170:173], v[50:53]
	v_mfma_f32_16x16x32_bf16 v[38:41], v[154:157], v[178:181], v[38:41]
	v_mfma_f32_16x16x32_bf16 v[34:37], v[162:165], v[178:181], v[34:37]
	v_mfma_f32_16x16x32_bf16 v[22:25], v[154:157], v[186:189], v[22:25]
	v_mfma_f32_16x16x32_bf16 v[18:21], v[162:165], v[186:189], v[18:21]
	v_mfma_f32_16x16x32_bf16 v[6:9], v[154:157], v[228:231], v[6:9]
	v_mfma_f32_16x16x32_bf16 v[2:5], v[162:165], v[228:231], v[2:5]
	v_mfma_f32_16x16x32_bf16 v[54:57], v[158:161], v[174:177], v[54:57]
	v_mfma_f32_16x16x32_bf16 v[50:53], v[166:169], v[174:177], v[50:53]
	v_mfma_f32_16x16x32_bf16 v[38:41], v[158:161], v[182:185], v[38:41]
	v_mfma_f32_16x16x32_bf16 v[34:37], v[166:169], v[182:185], v[34:37]
	v_mfma_f32_16x16x32_bf16 v[22:25], v[158:161], v[216:219], v[22:25]
	v_mfma_f32_16x16x32_bf16 v[18:21], v[166:169], v[216:219], v[18:21]
	v_mfma_f32_16x16x32_bf16 v[6:9], v[158:161], v[232:235], v[6:9]
	v_mfma_f32_16x16x32_bf16 v[2:5], v[166:169], v[232:235], v[2:5]
	s_setprio 0
	s_barrier
	s_add_i32 s73, s73, 2
	s_add_u32 s55, s55, 0x100
	s_addc_u32 s71, s71, 0
	s_add_u32 s24, s24, 0x100
	s_addc_u32 s25, s25, 0
	s_cmp_gt_u32 s73, 13
	s_cbranch_scc0 .LBB0_126
	s_and_b64 vcc, exec, s[44:45]
	s_cbranch_vccz .LBB0_129
	s_barrier
.LBB0_129:
	s_lshl_b32 s0, s4, 8
	s_add_i32 s0, s0, s89
	v_and_or_b32 v0, v193, 15, s0
	v_bfe_u32 v146, v193, 4, 2
	s_lshr_b32 s29, s0, 11
	s_cmp_eq_u32 s28, 2
	s_cselect_b64 s[40:41], -1, 0
	s_and_b64 s[40:41], s[40:41], s[78:79]
	s_cmp_lg_u64 s[40:41], 0
	s_cbranch_scc0 .Llat_norope1
	v_lshlrev_b32_e32 v131, 6, v0
	v_lshl_add_u32 v131, v146, 4, v131
	v_add_u32_e32 v132, 0x2000, v131
	global_load_dwordx4 v[142:145], v131, s[14:15]
	global_load_dwordx4 v[148:151], v131, s[16:17]
	global_load_dwordx4 v[152:155], v131, s[14:15] offset:1024
	global_load_dwordx4 v[156:159], v131, s[16:17] offset:1024
	global_load_dwordx4 v[160:163], v131, s[14:15] offset:2048
	global_load_dwordx4 v[164:167], v131, s[16:17] offset:2048
	global_load_dwordx4 v[168:171], v131, s[14:15] offset:3072
	global_load_dwordx4 v[172:175], v131, s[16:17] offset:3072
	global_load_dwordx4 v[176:179], v132, s[14:15]
	global_load_dwordx4 v[180:183], v132, s[16:17]
	global_load_dwordx4 v[184:187], v132, s[14:15] offset:1024
	global_load_dwordx4 v[188:191], v132, s[16:17] offset:1024
	global_load_dwordx4 v[216:219], v132, s[14:15] offset:2048
	global_load_dwordx4 v[228:231], v132, s[16:17] offset:2048
	global_load_dwordx4 v[232:235], v132, s[14:15] offset:3072
	global_load_dwordx4 v[236:239], v132, s[16:17] offset:3072
.Llat_norope1:
	v_add_f32_e32 v194, v195, v194
	v_add_f32_e32 v196, v196, v197
	v_add_f32_e32 v198, v199, v198
	v_add_f32_e32 v200, v200, v201
	v_add_f32_e32 v202, v203, v202
	v_add_f32_e32 v204, v204, v205
	v_add_f32_e32 v206, v207, v206
	v_add_f32_e32 v208, v208, v209
	v_add_f32_e32 v194, v194, v196
	v_add_f32_e32 v198, v198, v200
	v_add_f32_e32 v202, v202, v204
	v_add_f32_e32 v206, v206, v208
	ds_swizzle_b32 v195, v221 offset:swizzle(SWAP,16)
	ds_swizzle_b32 v196, v222 offset:swizzle(SWAP,16)
	ds_swizzle_b32 v199, v223 offset:swizzle(SWAP,16)
	ds_swizzle_b32 v200, v224 offset:swizzle(SWAP,16)
	ds_swizzle_b32 v203, v194 offset:swizzle(SWAP,16)
	ds_swizzle_b32 v204, v198 offset:swizzle(SWAP,16)
	ds_swizzle_b32 v207, v202 offset:swizzle(SWAP,16)
	ds_swizzle_b32 v208, v206 offset:swizzle(SWAP,16)
	s_waitcnt lgkmcnt(0)
	v_add_f32_e32 v221, v221, v195
	v_add_f32_e32 v222, v222, v196
	v_add_f32_e32 v223, v223, v199
	v_add_f32_e32 v224, v224, v200
	v_add_f32_e32 v194, v194, v203
	v_add_f32_e32 v198, v198, v204
	v_add_f32_e32 v202, v202, v207
	v_add_f32_e32 v206, v206, v208
	v_mov_b32_e32 v197, v221
	v_mov_b32_e32 v201, v222
	v_mov_b32_e32 v205, v223
	v_mov_b32_e32 v209, v224
	v_mov_b32_e32 v240, v194
	v_mov_b32_e32 v241, v198
	v_mov_b32_e32 v242, v202
	v_mov_b32_e32 v243, v206
	v_permlane32_swap_b32_e32 v221, v197
	v_permlane32_swap_b32_e32 v222, v201
	v_permlane32_swap_b32_e32 v223, v205
	v_permlane32_swap_b32_e32 v224, v209
	v_permlane32_swap_b32_e32 v194, v240
	v_permlane32_swap_b32_e32 v198, v241
	v_permlane32_swap_b32_e32 v202, v242
	v_permlane32_swap_b32_e32 v206, v243
	v_add_f32_e32 v221, v221, v197
	v_add_f32_e32 v222, v222, v201
	v_add_f32_e32 v223, v223, v205
	v_add_f32_e32 v224, v224, v209
	v_add_f32_e32 v194, v194, v240
	v_add_f32_e32 v198, v198, v241
	v_add_f32_e32 v202, v202, v242
	v_add_f32_e32 v206, v206, v243
	v_fmamk_f32 v221, v221, 0x3a800000, v192
	v_fmamk_f32 v222, v222, 0x3a800000, v192
	v_fmamk_f32 v223, v223, 0x3a800000, v192
	v_fmamk_f32 v224, v224, 0x3a800000, v192
	v_fmamk_f32 v194, v194, 0x3a800000, v192
	v_fmamk_f32 v198, v198, 0x3a800000, v192
	v_fmamk_f32 v202, v202, 0x3a800000, v192
	v_fmamk_f32 v206, v206, 0x3a800000, v192
	v_rsq_f32_e32 v221, v221
	v_rsq_f32_e32 v222, v222
	v_rsq_f32_e32 v223, v223
	v_rsq_f32_e32 v224, v224
	v_rsq_f32_e32 v194, v194
	v_rsq_f32_e32 v198, v198
	v_rsq_f32_e32 v202, v202
	v_rsq_f32_e32 v206, v206
	v_pk_mul_f32 v[126:127], v[126:127], v[220:221] op_sel:[0,1] op_sel_hi:[1,1]
	v_pk_mul_f32 v[128:129], v[128:129], v[220:221] op_sel:[0,1] op_sel_hi:[1,1]
	v_pk_mul_f32 v[122:123], v[122:123], v[220:221] op_sel:[0,1] op_sel_hi:[1,1]
	v_pk_mul_f32 v[124:125], v[124:125], v[220:221] op_sel:[0,1] op_sel_hi:[1,1]
	v_pk_mul_f32 v[118:119], v[118:119], v[220:221] op_sel:[0,1] op_sel_hi:[1,1]
	v_pk_mul_f32 v[120:121], v[120:121], v[220:221] op_sel:[0,1] op_sel_hi:[1,1]
	v_pk_mul_f32 v[114:115], v[114:115], v[220:221] op_sel:[0,1] op_sel_hi:[1,1]
	v_pk_mul_f32 v[116:117], v[116:117], v[220:221] op_sel:[0,1] op_sel_hi:[1,1]
	v_pk_mul_f32 v[110:111], v[110:111], v[222:223] op_sel_hi:[1,0]
	v_pk_mul_f32 v[112:113], v[112:113], v[222:223] op_sel_hi:[1,0]
	v_pk_mul_f32 v[106:107], v[106:107], v[222:223] op_sel_hi:[1,0]
	v_pk_mul_f32 v[108:109], v[108:109], v[222:223] op_sel_hi:[1,0]
	v_pk_mul_f32 v[102:103], v[102:103], v[222:223] op_sel_hi:[1,0]
	v_pk_mul_f32 v[104:105], v[104:105], v[222:223] op_sel_hi:[1,0]
	v_pk_mul_f32 v[98:99], v[98:99], v[222:223] op_sel_hi:[1,0]
	v_pk_mul_f32 v[100:101], v[100:101], v[222:223] op_sel_hi:[1,0]
	v_pk_mul_f32 v[94:95], v[94:95], v[222:223] op_sel:[0,1] op_sel_hi:[1,1]
	v_pk_mul_f32 v[96:97], v[96:97], v[222:223] op_sel:[0,1] op_sel_hi:[1,1]
	v_pk_mul_f32 v[90:91], v[90:91], v[222:223] op_sel:[0,1] op_sel_hi:[1,1]
	v_pk_mul_f32 v[92:93], v[92:93], v[222:223] op_sel:[0,1] op_sel_hi:[1,1]
	v_pk_mul_f32 v[86:87], v[86:87], v[222:223] op_sel:[0,1] op_sel_hi:[1,1]
	v_pk_mul_f32 v[88:89], v[88:89], v[222:223] op_sel:[0,1] op_sel_hi:[1,1]
	v_pk_mul_f32 v[82:83], v[82:83], v[222:223] op_sel:[0,1] op_sel_hi:[1,1]
	v_pk_mul_f32 v[84:85], v[84:85], v[222:223] op_sel:[0,1] op_sel_hi:[1,1]
	v_pk_mul_f32 v[78:79], v[78:79], v[224:225] op_sel_hi:[1,0]
	v_pk_mul_f32 v[80:81], v[80:81], v[224:225] op_sel_hi:[1,0]
	v_pk_mul_f32 v[74:75], v[74:75], v[224:225] op_sel_hi:[1,0]
	v_pk_mul_f32 v[76:77], v[76:77], v[224:225] op_sel_hi:[1,0]
	v_pk_mul_f32 v[70:71], v[70:71], v[224:225] op_sel_hi:[1,0]
	v_pk_mul_f32 v[72:73], v[72:73], v[224:225] op_sel_hi:[1,0]
	v_pk_mul_f32 v[66:67], v[66:67], v[224:225] op_sel_hi:[1,0]
	v_pk_mul_f32 v[68:69], v[68:69], v[224:225] op_sel_hi:[1,0]
	v_pk_mul_f32 v[62:63], v[62:63], v[194:195] op_sel_hi:[1,0]
	v_pk_mul_f32 v[64:65], v[64:65], v[194:195] op_sel_hi:[1,0]
	v_pk_mul_f32 v[58:59], v[58:59], v[194:195] op_sel_hi:[1,0]
	v_pk_mul_f32 v[60:61], v[60:61], v[194:195] op_sel_hi:[1,0]
	v_pk_mul_f32 v[54:55], v[54:55], v[194:195] op_sel_hi:[1,0]
	v_pk_mul_f32 v[56:57], v[56:57], v[194:195] op_sel_hi:[1,0]
	v_pk_mul_f32 v[50:51], v[50:51], v[194:195] op_sel_hi:[1,0]
	v_pk_mul_f32 v[52:53], v[52:53], v[194:195] op_sel_hi:[1,0]
	v_pk_mul_f32 v[46:47], v[46:47], v[198:199] op_sel_hi:[1,0]
	v_pk_mul_f32 v[48:49], v[48:49], v[198:199] op_sel_hi:[1,0]
	v_pk_mul_f32 v[42:43], v[42:43], v[198:199] op_sel_hi:[1,0]
	v_pk_mul_f32 v[44:45], v[44:45], v[198:199] op_sel_hi:[1,0]
	v_pk_mul_f32 v[38:39], v[38:39], v[198:199] op_sel_hi:[1,0]
	v_pk_mul_f32 v[40:41], v[40:41], v[198:199] op_sel_hi:[1,0]
	v_pk_mul_f32 v[34:35], v[34:35], v[198:199] op_sel_hi:[1,0]
	v_pk_mul_f32 v[36:37], v[36:37], v[198:199] op_sel_hi:[1,0]
	v_pk_mul_f32 v[30:31], v[30:31], v[202:203] op_sel_hi:[1,0]
	v_pk_mul_f32 v[32:33], v[32:33], v[202:203] op_sel_hi:[1,0]
	v_pk_mul_f32 v[26:27], v[26:27], v[202:203] op_sel_hi:[1,0]
	v_pk_mul_f32 v[28:29], v[28:29], v[202:203] op_sel_hi:[1,0]
	v_pk_mul_f32 v[22:23], v[22:23], v[202:203] op_sel_hi:[1,0]
	v_pk_mul_f32 v[24:25], v[24:25], v[202:203] op_sel_hi:[1,0]
	v_pk_mul_f32 v[18:19], v[18:19], v[202:203] op_sel_hi:[1,0]
	v_pk_mul_f32 v[20:21], v[20:21], v[202:203] op_sel_hi:[1,0]
	v_pk_mul_f32 v[14:15], v[14:15], v[206:207] op_sel_hi:[1,0]
	v_pk_mul_f32 v[16:17], v[16:17], v[206:207] op_sel_hi:[1,0]
	v_pk_mul_f32 v[10:11], v[10:11], v[206:207] op_sel_hi:[1,0]
	v_pk_mul_f32 v[12:13], v[12:13], v[206:207] op_sel_hi:[1,0]
	v_pk_mul_f32 v[6:7], v[6:7], v[206:207] op_sel_hi:[1,0]
	v_pk_mul_f32 v[8:9], v[8:9], v[206:207] op_sel_hi:[1,0]
	v_pk_mul_f32 v[2:3], v[2:3], v[206:207] op_sel_hi:[1,0]
	v_pk_mul_f32 v[4:5], v[4:5], v[206:207] op_sel_hi:[1,0]
	s_cmp_lg_u64 s[40:41], 0
	s_cbranch_scc0 .Llat_norope2
	v_lshrrev_b32_e32 v131, 1, v146
	s_lshl_b32 s0, s29, 2
	v_add_u32_e32 v131, s0, v131
	v_lshlrev_b32_e32 v131, 15, v131
	v_and_b32_e32 v132, 0x7ff, v0
	v_lshl_add_u32 v131, v132, 4, v131
	v_and_b32_e32 v132, 1, v146
	v_lshl_add_u32 v131, v132, 3, v131
	v_add_u32_e32 v132, 0x10000, v131
	s_waitcnt vmcnt(0)
	v_pk_mul_f32 v[194:195], v[114:115], v[148:149]
	v_pk_mul_f32 v[196:197], v[116:117], v[150:151]
	v_pk_fma_f32 v[194:195], v[118:119], v[142:143], v[194:195] neg_lo:[0,0,1] neg_hi:[0,0,1]
	v_pk_fma_f32 v[196:197], v[120:121], v[144:145], v[196:197] neg_lo:[0,0,1] neg_hi:[0,0,1]
	v_cvt_pk_bf16_f32 v198, v194, v195
	v_cvt_pk_bf16_f32 v199, v196, v197
	global_store_dwordx2 v131, v[198:199], s[12:13]
	v_pk_mul_f32 v[194:195], v[114:115], v[142:143]
	v_pk_mul_f32 v[196:197], v[116:117], v[144:145]
	v_pk_fma_f32 v[194:195], v[118:119], v[148:149], v[194:195]
	v_pk_fma_f32 v[196:197], v[120:121], v[150:151], v[196:197]
	v_cvt_pk_bf16_f32 v200, v194, v195
	v_cvt_pk_bf16_f32 v201, v196, v197
	global_store_dwordx2 v132, v[200:201], s[12:13]
	v_pk_mul_f32 v[202:203], v[98:99], v[156:157]
	v_pk_mul_f32 v[204:205], v[100:101], v[158:159]
	v_pk_fma_f32 v[202:203], v[102:103], v[152:153], v[202:203] neg_lo:[0,0,1] neg_hi:[0,0,1]
	v_pk_fma_f32 v[204:205], v[104:105], v[154:155], v[204:205] neg_lo:[0,0,1] neg_hi:[0,0,1]
	v_cvt_pk_bf16_f32 v206, v202, v203
	v_cvt_pk_bf16_f32 v207, v204, v205
	global_store_dwordx2 v131, v[206:207], s[12:13] offset:256
	v_pk_mul_f32 v[202:203], v[98:99], v[152:153]
	v_pk_mul_f32 v[204:205], v[100:101], v[154:155]
	v_pk_fma_f32 v[202:203], v[102:103], v[156:157], v[202:203]
	v_pk_fma_f32 v[204:205], v[104:105], v[158:159], v[204:205]
	v_cvt_pk_bf16_f32 v208, v202, v203
	v_cvt_pk_bf16_f32 v209, v204, v205
	global_store_dwordx2 v132, v[208:209], s[12:13] offset:256
	v_pk_mul_f32 v[194:195], v[82:83], v[164:165]
	v_pk_mul_f32 v[196:197], v[84:85], v[166:167]
	v_pk_fma_f32 v[194:195], v[86:87], v[160:161], v[194:195] neg_lo:[0,0,1] neg_hi:[0,0,1]
	v_pk_fma_f32 v[196:197], v[88:89], v[162:163], v[196:197] neg_lo:[0,0,1] neg_hi:[0,0,1]
	v_cvt_pk_bf16_f32 v198, v194, v195
	v_cvt_pk_bf16_f32 v199, v196, v197
	global_store_dwordx2 v131, v[198:199], s[12:13] offset:512
	v_pk_mul_f32 v[194:195], v[82:83], v[160:161]
	v_pk_mul_f32 v[196:197], v[84:85], v[162:163]
	v_pk_fma_f32 v[194:195], v[86:87], v[164:165], v[194:195]
	v_pk_fma_f32 v[196:197], v[88:89], v[166:167], v[196:197]
	v_cvt_pk_bf16_f32 v200, v194, v195
	v_cvt_pk_bf16_f32 v201, v196, v197
	global_store_dwordx2 v132, v[200:201], s[12:13] offset:512
	v_pk_mul_f32 v[202:203], v[66:67], v[172:173]
	v_pk_mul_f32 v[204:205], v[68:69], v[174:175]
	v_pk_fma_f32 v[202:203], v[70:71], v[168:169], v[202:203] neg_lo:[0,0,1] neg_hi:[0,0,1]
	v_pk_fma_f32 v[204:205], v[72:73], v[170:171], v[204:205] neg_lo:[0,0,1] neg_hi:[0,0,1]
	v_cvt_pk_bf16_f32 v206, v202, v203
	v_cvt_pk_bf16_f32 v207, v204, v205
	global_store_dwordx2 v131, v[206:207], s[12:13] offset:768
	v_pk_mul_f32 v[202:203], v[66:67], v[168:169]
	v_pk_mul_f32 v[204:205], v[68:69], v[170:171]
	v_pk_fma_f32 v[202:203], v[70:71], v[172:173], v[202:203]
	v_pk_fma_f32 v[204:205], v[72:73], v[174:175], v[204:205]
	v_cvt_pk_bf16_f32 v208, v202, v203
	v_cvt_pk_bf16_f32 v209, v204, v205
	global_store_dwordx2 v132, v[208:209], s[12:13] offset:768
	v_pk_mul_f32 v[194:195], v[50:51], v[180:181]
	v_pk_mul_f32 v[196:197], v[52:53], v[182:183]
	v_pk_fma_f32 v[194:195], v[54:55], v[176:177], v[194:195] neg_lo:[0,0,1] neg_hi:[0,0,1]
	v_pk_fma_f32 v[196:197], v[56:57], v[178:179], v[196:197] neg_lo:[0,0,1] neg_hi:[0,0,1]
	v_cvt_pk_bf16_f32 v198, v194, v195
	v_cvt_pk_bf16_f32 v199, v196, v197
	global_store_dwordx2 v131, v[198:199], s[12:13] offset:2048
	v_pk_mul_f32 v[194:195], v[50:51], v[176:177]
	v_pk_mul_f32 v[196:197], v[52:53], v[178:179]
	v_pk_fma_f32 v[194:195], v[54:55], v[180:181], v[194:195]
	v_pk_fma_f32 v[196:197], v[56:57], v[182:183], v[196:197]
	v_cvt_pk_bf16_f32 v200, v194, v195
	v_cvt_pk_bf16_f32 v201, v196, v197
	global_store_dwordx2 v132, v[200:201], s[12:13] offset:2048
	v_pk_mul_f32 v[202:203], v[34:35], v[188:189]
	v_pk_mul_f32 v[204:205], v[36:37], v[190:191]
	v_pk_fma_f32 v[202:203], v[38:39], v[184:185], v[202:203] neg_lo:[0,0,1] neg_hi:[0,0,1]
	v_pk_fma_f32 v[204:205], v[40:41], v[186:187], v[204:205] neg_lo:[0,0,1] neg_hi:[0,0,1]
	v_cvt_pk_bf16_f32 v206, v202, v203
	v_cvt_pk_bf16_f32 v207, v204, v205
	global_store_dwordx2 v131, v[206:207], s[12:13] offset:2304
	v_pk_mul_f32 v[202:203], v[34:35], v[184:185]
	v_pk_mul_f32 v[204:205], v[36:37], v[186:187]
	v_pk_fma_f32 v[202:203], v[38:39], v[188:189], v[202:203]
	v_pk_fma_f32 v[204:205], v[40:41], v[190:191], v[204:205]
	v_cvt_pk_bf16_f32 v208, v202, v203
	v_cvt_pk_bf16_f32 v209, v204, v205
	global_store_dwordx2 v132, v[208:209], s[12:13] offset:2304
	v_pk_mul_f32 v[194:195], v[18:19], v[228:229]
	v_pk_mul_f32 v[196:197], v[20:21], v[230:231]
	v_pk_fma_f32 v[194:195], v[22:23], v[216:217], v[194:195] neg_lo:[0,0,1] neg_hi:[0,0,1]
	v_pk_fma_f32 v[196:197], v[24:25], v[218:219], v[196:197] neg_lo:[0,0,1] neg_hi:[0,0,1]
	v_cvt_pk_bf16_f32 v198, v194, v195
	v_cvt_pk_bf16_f32 v199, v196, v197
	global_store_dwordx2 v131, v[198:199], s[12:13] offset:2560
	v_pk_mul_f32 v[194:195], v[18:19], v[216:217]
	v_pk_mul_f32 v[196:197], v[20:21], v[218:219]
	v_pk_fma_f32 v[194:195], v[22:23], v[228:229], v[194:195]
	v_pk_fma_f32 v[196:197], v[24:25], v[230:231], v[196:197]
	v_cvt_pk_bf16_f32 v200, v194, v195
	v_cvt_pk_bf16_f32 v201, v196, v197
	global_store_dwordx2 v132, v[200:201], s[12:13] offset:2560
	v_pk_mul_f32 v[202:203], v[2:3], v[236:237]
	v_pk_mul_f32 v[204:205], v[4:5], v[238:239]
	v_pk_fma_f32 v[202:203], v[6:7], v[232:233], v[202:203] neg_lo:[0,0,1] neg_hi:[0,0,1]
	v_pk_fma_f32 v[204:205], v[8:9], v[234:235], v[204:205] neg_lo:[0,0,1] neg_hi:[0,0,1]
	v_cvt_pk_bf16_f32 v206, v202, v203
	v_cvt_pk_bf16_f32 v207, v204, v205
	global_store_dwordx2 v131, v[206:207], s[12:13] offset:2816
	v_pk_mul_f32 v[202:203], v[2:3], v[232:233]
	v_pk_mul_f32 v[204:205], v[4:5], v[234:235]
	v_pk_fma_f32 v[202:203], v[6:7], v[236:237], v[202:203]
	v_pk_fma_f32 v[204:205], v[8:9], v[238:239], v[204:205]
	v_cvt_pk_bf16_f32 v208, v202, v203
	v_cvt_pk_bf16_f32 v209, v204, v205
	global_store_dwordx2 v132, v[208:209], s[12:13] offset:2816
.Llat_norope2:
	s_lshl_b32 s0, s28, 9
	s_lshl_b32 s24, s90, 1
	s_or_b32 s0, s0, s24
	v_lshl_or_b32 v130, v146, 3, s0
	v_mad_u32_u24 v130, v0, s46, v130
	s_lshl_b32 s0, s28, 5
	s_lshl_b32 s24, s88, 2
	s_or_b32 s0, s0, s24
	v_mov_b32_e32 v133, s0
	v_mad_u32_u24 v133, v0, s61, v133
	v_add_u32_e32 v131, 0x0, v130
	v_pk_mul_f32 v[142:143], v[126:127], v[126:127]
	v_pk_fma_f32 v[142:143], v[128:129], v[128:129], v[142:143]
	v_pk_fma_f32 v[142:143], v[122:123], v[122:123], v[142:143]
	v_pk_fma_f32 v[142:143], v[124:125], v[124:125], v[142:143]
	v_cvt_pk_bf16_f32 v126, v126, v127
	v_cvt_pk_bf16_f32 v127, v128, v129
	v_cvt_pk_bf16_f32 v122, v122, v123
	v_cvt_pk_bf16_f32 v123, v124, v125
	v_add_f32_e32 v150, v142, v143
	global_store_dwordx2 v131, v[126:127], s[8:9]
	global_store_dwordx2 v131, v[122:123], s[8:9] offset:32
	v_pk_mul_f32 v[148:149], v[118:119], v[118:119]
	v_pk_fma_f32 v[148:149], v[120:121], v[120:121], v[148:149]
	v_pk_fma_f32 v[148:149], v[114:115], v[114:115], v[148:149]
	v_pk_fma_f32 v[148:149], v[116:117], v[116:117], v[148:149]
	v_cvt_pk_bf16_f32 v118, v118, v119
	v_cvt_pk_bf16_f32 v119, v120, v121
	v_cvt_pk_bf16_f32 v114, v114, v115
	v_cvt_pk_bf16_f32 v115, v116, v117
	v_add_f32_e32 v151, v148, v149
	global_store_dwordx2 v131, v[118:119], s[8:9] offset:256
	global_store_dwordx2 v131, v[114:115], s[8:9] offset:288
	v_add_u32_e32 v132, 0x6000, v130
	v_pk_mul_f32 v[142:143], v[110:111], v[110:111]
	v_pk_fma_f32 v[142:143], v[112:113], v[112:113], v[142:143]
	v_pk_fma_f32 v[142:143], v[106:107], v[106:107], v[142:143]
	v_pk_fma_f32 v[142:143], v[108:109], v[108:109], v[142:143]
	v_cvt_pk_bf16_f32 v110, v110, v111
	v_cvt_pk_bf16_f32 v111, v112, v113
	v_cvt_pk_bf16_f32 v106, v106, v107
	v_cvt_pk_bf16_f32 v107, v108, v109
	v_add_f32_e32 v152, v142, v143
	global_store_dwordx2 v132, v[110:111], s[8:9]
	global_store_dwordx2 v132, v[106:107], s[8:9] offset:32
	v_pk_mul_f32 v[148:149], v[102:103], v[102:103]
	v_pk_fma_f32 v[148:149], v[104:105], v[104:105], v[148:149]
	v_pk_fma_f32 v[148:149], v[98:99], v[98:99], v[148:149]
	v_pk_fma_f32 v[148:149], v[100:101], v[100:101], v[148:149]
	v_cvt_pk_bf16_f32 v102, v102, v103
	v_cvt_pk_bf16_f32 v103, v104, v105
	v_cvt_pk_bf16_f32 v98, v98, v99
	v_cvt_pk_bf16_f32 v99, v100, v101
	v_add_f32_e32 v153, v148, v149
	global_store_dwordx2 v132, v[102:103], s[8:9] offset:256
	global_store_dwordx2 v132, v[98:99], s[8:9] offset:288
	v_add_u32_e32 v131, 0xc000, v130
	v_pk_mul_f32 v[142:143], v[94:95], v[94:95]
	v_pk_fma_f32 v[142:143], v[96:97], v[96:97], v[142:143]
	v_pk_fma_f32 v[142:143], v[90:91], v[90:91], v[142:143]
	v_pk_fma_f32 v[142:143], v[92:93], v[92:93], v[142:143]
	v_cvt_pk_bf16_f32 v94, v94, v95
	v_cvt_pk_bf16_f32 v95, v96, v97
	v_cvt_pk_bf16_f32 v90, v90, v91
	v_cvt_pk_bf16_f32 v91, v92, v93
	v_add_f32_e32 v154, v142, v143
	global_store_dwordx2 v131, v[94:95], s[8:9]
	global_store_dwordx2 v131, v[90:91], s[8:9] offset:32
	v_pk_mul_f32 v[148:149], v[86:87], v[86:87]
	v_pk_fma_f32 v[148:149], v[88:89], v[88:89], v[148:149]
	v_pk_fma_f32 v[148:149], v[82:83], v[82:83], v[148:149]
	v_pk_fma_f32 v[148:149], v[84:85], v[84:85], v[148:149]
	v_cvt_pk_bf16_f32 v86, v86, v87
	v_cvt_pk_bf16_f32 v87, v88, v89
	v_cvt_pk_bf16_f32 v82, v82, v83
	v_cvt_pk_bf16_f32 v83, v84, v85
	v_add_f32_e32 v155, v148, v149
	global_store_dwordx2 v131, v[86:87], s[8:9] offset:256
	global_store_dwordx2 v131, v[82:83], s[8:9] offset:288
	v_add_u32_e32 v132, 0x12000, v130
	v_pk_mul_f32 v[142:143], v[78:79], v[78:79]
	v_pk_fma_f32 v[142:143], v[80:81], v[80:81], v[142:143]
	v_pk_fma_f32 v[142:143], v[74:75], v[74:75], v[142:143]
	v_pk_fma_f32 v[142:143], v[76:77], v[76:77], v[142:143]
	v_cvt_pk_bf16_f32 v78, v78, v79
	v_cvt_pk_bf16_f32 v79, v80, v81
	v_cvt_pk_bf16_f32 v74, v74, v75
	v_cvt_pk_bf16_f32 v75, v76, v77
	v_add_f32_e32 v156, v142, v143
	global_store_dwordx2 v132, v[78:79], s[8:9]
	global_store_dwordx2 v132, v[74:75], s[8:9] offset:32
	v_pk_mul_f32 v[148:149], v[70:71], v[70:71]
	v_pk_fma_f32 v[148:149], v[72:73], v[72:73], v[148:149]
	v_pk_fma_f32 v[148:149], v[66:67], v[66:67], v[148:149]
	v_pk_fma_f32 v[148:149], v[68:69], v[68:69], v[148:149]
	v_cvt_pk_bf16_f32 v70, v70, v71
	v_cvt_pk_bf16_f32 v71, v72, v73
	v_cvt_pk_bf16_f32 v66, v66, v67
	v_cvt_pk_bf16_f32 v67, v68, v69
	v_add_f32_e32 v157, v148, v149
	global_store_dwordx2 v132, v[70:71], s[8:9] offset:256
	global_store_dwordx2 v132, v[66:67], s[8:9] offset:288
	v_add_u32_e32 v131, 0x30000, v130
	v_pk_mul_f32 v[142:143], v[62:63], v[62:63]
	v_pk_fma_f32 v[142:143], v[64:65], v[64:65], v[142:143]
	v_pk_fma_f32 v[142:143], v[58:59], v[58:59], v[142:143]
	v_pk_fma_f32 v[142:143], v[60:61], v[60:61], v[142:143]
	v_cvt_pk_bf16_f32 v62, v62, v63
	v_cvt_pk_bf16_f32 v63, v64, v65
	v_cvt_pk_bf16_f32 v58, v58, v59
	v_cvt_pk_bf16_f32 v59, v60, v61
	v_add_f32_e32 v158, v142, v143
	global_store_dwordx2 v131, v[62:63], s[8:9]
	global_store_dwordx2 v131, v[58:59], s[8:9] offset:32
	v_pk_mul_f32 v[148:149], v[54:55], v[54:55]
	v_pk_fma_f32 v[148:149], v[56:57], v[56:57], v[148:149]
	v_pk_fma_f32 v[148:149], v[50:51], v[50:51], v[148:149]
	v_pk_fma_f32 v[148:149], v[52:53], v[52:53], v[148:149]
	v_cvt_pk_bf16_f32 v54, v54, v55
	v_cvt_pk_bf16_f32 v55, v56, v57
	v_cvt_pk_bf16_f32 v50, v50, v51
	v_cvt_pk_bf16_f32 v51, v52, v53
	v_add_f32_e32 v159, v148, v149
	global_store_dwordx2 v131, v[54:55], s[8:9] offset:256
	global_store_dwordx2 v131, v[50:51], s[8:9] offset:288
	v_add_u32_e32 v132, 0x36000, v130
	v_pk_mul_f32 v[142:143], v[46:47], v[46:47]
	v_pk_fma_f32 v[142:143], v[48:49], v[48:49], v[142:143]
	v_pk_fma_f32 v[142:143], v[42:43], v[42:43], v[142:143]
	v_pk_fma_f32 v[142:143], v[44:45], v[44:45], v[142:143]
	v_cvt_pk_bf16_f32 v46, v46, v47
	v_cvt_pk_bf16_f32 v47, v48, v49
	v_cvt_pk_bf16_f32 v42, v42, v43
	v_cvt_pk_bf16_f32 v43, v44, v45
	v_add_f32_e32 v160, v142, v143
	global_store_dwordx2 v132, v[46:47], s[8:9]
	global_store_dwordx2 v132, v[42:43], s[8:9] offset:32
	v_pk_mul_f32 v[148:149], v[38:39], v[38:39]
	v_pk_fma_f32 v[148:149], v[40:41], v[40:41], v[148:149]
	v_pk_fma_f32 v[148:149], v[34:35], v[34:35], v[148:149]
	v_pk_fma_f32 v[148:149], v[36:37], v[36:37], v[148:149]
	v_cvt_pk_bf16_f32 v38, v38, v39
	v_cvt_pk_bf16_f32 v39, v40, v41
	v_cvt_pk_bf16_f32 v34, v34, v35
	v_cvt_pk_bf16_f32 v35, v36, v37
	v_add_f32_e32 v161, v148, v149
	global_store_dwordx2 v132, v[38:39], s[8:9] offset:256
	global_store_dwordx2 v132, v[34:35], s[8:9] offset:288
	v_add_u32_e32 v131, 0x3c000, v130
	v_pk_mul_f32 v[142:143], v[30:31], v[30:31]
	v_pk_fma_f32 v[142:143], v[32:33], v[32:33], v[142:143]
	v_pk_fma_f32 v[142:143], v[26:27], v[26:27], v[142:143]
	v_pk_fma_f32 v[142:143], v[28:29], v[28:29], v[142:143]
	v_cvt_pk_bf16_f32 v30, v30, v31
	v_cvt_pk_bf16_f32 v31, v32, v33
	v_cvt_pk_bf16_f32 v26, v26, v27
	v_cvt_pk_bf16_f32 v27, v28, v29
	v_add_f32_e32 v162, v142, v143
	global_store_dwordx2 v131, v[30:31], s[8:9]
	global_store_dwordx2 v131, v[26:27], s[8:9] offset:32
	v_pk_mul_f32 v[148:149], v[22:23], v[22:23]
	v_pk_fma_f32 v[148:149], v[24:25], v[24:25], v[148:149]
	v_pk_fma_f32 v[148:149], v[18:19], v[18:19], v[148:149]
	v_pk_fma_f32 v[148:149], v[20:21], v[20:21], v[148:149]
	v_cvt_pk_bf16_f32 v22, v22, v23
	v_cvt_pk_bf16_f32 v23, v24, v25
	v_cvt_pk_bf16_f32 v18, v18, v19
	v_cvt_pk_bf16_f32 v19, v20, v21
	v_add_f32_e32 v163, v148, v149
	global_store_dwordx2 v131, v[22:23], s[8:9] offset:256
	global_store_dwordx2 v131, v[18:19], s[8:9] offset:288
	v_add_u32_e32 v132, 0x42000, v130
	v_pk_mul_f32 v[142:143], v[14:15], v[14:15]
	v_pk_fma_f32 v[142:143], v[16:17], v[16:17], v[142:143]
	v_pk_fma_f32 v[142:143], v[10:11], v[10:11], v[142:143]
	v_pk_fma_f32 v[142:143], v[12:13], v[12:13], v[142:143]
	v_cvt_pk_bf16_f32 v14, v14, v15
	v_cvt_pk_bf16_f32 v15, v16, v17
	v_cvt_pk_bf16_f32 v10, v10, v11
	v_cvt_pk_bf16_f32 v11, v12, v13
	v_add_f32_e32 v164, v142, v143
	global_store_dwordx2 v132, v[14:15], s[8:9]
	global_store_dwordx2 v132, v[10:11], s[8:9] offset:32
	v_pk_mul_f32 v[148:149], v[6:7], v[6:7]
	v_pk_fma_f32 v[148:149], v[8:9], v[8:9], v[148:149]
	v_pk_fma_f32 v[148:149], v[2:3], v[2:3], v[148:149]
	v_pk_fma_f32 v[148:149], v[4:5], v[4:5], v[148:149]
	v_cvt_pk_bf16_f32 v6, v6, v7
	v_cvt_pk_bf16_f32 v7, v8, v9
	v_cvt_pk_bf16_f32 v2, v2, v3
	v_cvt_pk_bf16_f32 v3, v4, v5
	v_add_f32_e32 v165, v148, v149
	global_store_dwordx2 v132, v[6:7], s[8:9] offset:256
	global_store_dwordx2 v132, v[2:3], s[8:9] offset:288
	ds_swizzle_b32 v166, v150 offset:swizzle(SWAP,16)
	ds_swizzle_b32 v167, v151 offset:swizzle(SWAP,16)
	ds_swizzle_b32 v168, v152 offset:swizzle(SWAP,16)
	ds_swizzle_b32 v169, v153 offset:swizzle(SWAP,16)
	ds_swizzle_b32 v170, v154 offset:swizzle(SWAP,16)
	ds_swizzle_b32 v171, v155 offset:swizzle(SWAP,16)
	ds_swizzle_b32 v172, v156 offset:swizzle(SWAP,16)
	ds_swizzle_b32 v173, v157 offset:swizzle(SWAP,16)
	ds_swizzle_b32 v174, v158 offset:swizzle(SWAP,16)
	ds_swizzle_b32 v175, v159 offset:swizzle(SWAP,16)
	ds_swizzle_b32 v176, v160 offset:swizzle(SWAP,16)
	ds_swizzle_b32 v177, v161 offset:swizzle(SWAP,16)
	ds_swizzle_b32 v178, v162 offset:swizzle(SWAP,16)
	ds_swizzle_b32 v179, v163 offset:swizzle(SWAP,16)
	ds_swizzle_b32 v180, v164 offset:swizzle(SWAP,16)
	ds_swizzle_b32 v181, v165 offset:swizzle(SWAP,16)
	s_waitcnt lgkmcnt(0)
	v_add_f32_e32 v150, v150, v166
	v_add_f32_e32 v151, v151, v167
	v_add_f32_e32 v152, v152, v168
	v_add_f32_e32 v153, v153, v169
	v_add_f32_e32 v154, v154, v170
	v_add_f32_e32 v155, v155, v171
	v_add_f32_e32 v156, v156, v172
	v_add_f32_e32 v157, v157, v173
	v_add_f32_e32 v158, v158, v174
	v_add_f32_e32 v159, v159, v175
	v_add_f32_e32 v160, v160, v176
	v_add_f32_e32 v161, v161, v177
	v_add_f32_e32 v162, v162, v178
	v_add_f32_e32 v163, v163, v179
	v_add_f32_e32 v164, v164, v180
	v_add_f32_e32 v165, v165, v181
	v_mov_b32_e32 v182, v150
	v_mov_b32_e32 v183, v151
	v_mov_b32_e32 v184, v152
	v_mov_b32_e32 v185, v153
	v_mov_b32_e32 v186, v154
	v_mov_b32_e32 v187, v155
	v_mov_b32_e32 v188, v156
	v_mov_b32_e32 v189, v157
	v_mov_b32_e32 v228, v158
	v_mov_b32_e32 v229, v159
	v_mov_b32_e32 v230, v160
	v_mov_b32_e32 v231, v161
	v_mov_b32_e32 v232, v162
	v_mov_b32_e32 v233, v163
	v_mov_b32_e32 v234, v164
	v_mov_b32_e32 v235, v165
	v_permlane32_swap_b32_e32 v150, v182
	v_permlane32_swap_b32_e32 v151, v183
	v_permlane32_swap_b32_e32 v152, v184
	v_permlane32_swap_b32_e32 v153, v185
	v_permlane32_swap_b32_e32 v154, v186
	v_permlane32_swap_b32_e32 v155, v187
	v_permlane32_swap_b32_e32 v156, v188
	v_permlane32_swap_b32_e32 v157, v189
	v_permlane32_swap_b32_e32 v158, v228
	v_permlane32_swap_b32_e32 v159, v229
	v_permlane32_swap_b32_e32 v160, v230
	v_permlane32_swap_b32_e32 v161, v231
	v_permlane32_swap_b32_e32 v162, v232
	v_permlane32_swap_b32_e32 v163, v233
	v_permlane32_swap_b32_e32 v164, v234
	v_permlane32_swap_b32_e32 v165, v235
	v_add_f32_e32 v150, v150, v182
	v_add_f32_e32 v151, v151, v183
	v_add_f32_e32 v152, v152, v184
	v_add_f32_e32 v153, v153, v185
	v_add_f32_e32 v154, v154, v186
	v_add_f32_e32 v155, v155, v187
	v_add_f32_e32 v156, v156, v188
	v_add_f32_e32 v157, v157, v189
	v_add_f32_e32 v158, v158, v228
	v_add_f32_e32 v159, v159, v229
	v_add_f32_e32 v160, v160, v230
	v_add_f32_e32 v161, v161, v231
	v_add_f32_e32 v162, v162, v232
	v_add_f32_e32 v163, v163, v233
	v_add_f32_e32 v164, v164, v234
	v_add_f32_e32 v165, v165, v235
	s_mov_b64 exec, 0xffff
	v_add_u32_e32 v144, 0x0, v133
	global_store_dword v144, v150, s[10:11]
	global_store_dword v144, v151, s[10:11] offset:16
	v_add_u32_e32 v145, 0x600, v133
	global_store_dword v145, v152, s[10:11]
	global_store_dword v145, v153, s[10:11] offset:16
	v_add_u32_e32 v144, 0xc00, v133
	global_store_dword v144, v154, s[10:11]
	global_store_dword v144, v155, s[10:11] offset:16
	v_add_u32_e32 v145, 0x1200, v133
	global_store_dword v145, v156, s[10:11]
	global_store_dword v145, v157, s[10:11] offset:16
	v_add_u32_e32 v144, 0x3000, v133
	global_store_dword v144, v158, s[10:11]
	global_store_dword v144, v159, s[10:11] offset:16
	v_add_u32_e32 v145, 0x3600, v133
	global_store_dword v145, v160, s[10:11]
	global_store_dword v145, v161, s[10:11] offset:16
	v_add_u32_e32 v144, 0x3c00, v133
	global_store_dword v144, v162, s[10:11]
	global_store_dword v144, v163, s[10:11] offset:16
	v_add_u32_e32 v145, 0x4200, v133
	global_store_dword v145, v164, s[10:11]
	global_store_dword v145, v165, s[10:11] offset:16
	s_mov_b64 exec, -1
	v_mov_b64_e32 v[194:195], 0xc0
	v_mov_b64_e32 v[196:197], 0xbf
	v_mov_b64_e32 v[198:199], 0x180
	v_mov_b64_e32 v[200:201], 0x17f
	v_mov_b64_e32 v[202:203], 0x200
	v_mov_b64_e32 v[204:205], 0x1ff
	v_mov_b64_e32 v[206:207], 0x100
	v_mov_b64_e32 v[208:209], 0xff
	v_mov_b32_e32 v221, 0x3e38aa3b
	v_mov_b32_e32 v222, 0x7c
	v_mov_b32_e32 v223, 0x80
	v_mov_b32_e32 v224, 0x42800000
	s_andn2_b64 vcc, exec, s[36:37]
	s_mov_b64 s[24:25], -1
	s_cbranch_vccnz .LBB0_122
